# phase B epilogue of the NSA-gate column tile: 8 row scales fetched together (as head tiles)
# speedup vs baseline: 1.0017x; 1.0017x over previous
; __device__ __forceinline__ float sigmoidf_(float x) { return __builtin_amdgcn_rcpf(1.0f + __expf(-x)); }
;     __device__ __forceinline__ void operator()(const f32x4 (&acc)[2][2][4][2], const pg8::Unit& u, int wr, int wc, int fr_, int fq_) const {
;     ...
;         } else if (t == 11) {
;             if (wc == 0 && fq < 3) {
; #pragma unroll
;                 for (int ai = 0; ai < 2; ++ai)
; #pragma unroll
;                     for (int m = 0; m < 4; ++m) { const unsigned row = (unsigned)(u.pm * 256 + 128 * ai + 64 * wr + 16 * m + fr);
;                         const float rin = rsq ? __builtin_amdgcn_rsqf(rsq[row] * (1.0f / DM) + 1e-6f) : 1.0f;
; #pragma unroll
;                         for (int n = 0; n < 2; ++n) { f32x4 y;
; #pragma unroll
;                             for (int e = 0; e < 4; ++e) y[e] = sigmoidf_(acc[ai][0][m][n][e] * rin);
;                             *(f32x4*)(nsg + (row * 24u + (unsigned)(8 * fq + 4 * n))) = y; } }
;             }
.LBB0_456:
	s_and_b64 vcc, exec, s[6:7]
	s_cbranch_vccz .LBB0_476
	v_cmp_gt_i32_e32 vcc, 3, v157
	s_and_b64 s[6:7], s[18:19], vcc
	s_and_saveexec_b64 s[40:41], s[6:7]
	s_cbranch_execz .LBB0_475
	s_lshl_b32 s6, s38, 8
	s_add_i32 s6, s6, s64
	v_cndmask_b32_e64 v80, 0, 1, s[8:9]
	v_add_u32_e32 v138, s6, v142
	v_mov_b32_e32 v143, 1.0
	v_cmp_ne_u32_e64 s[6:7], 1, v80
	s_andn2_b64 vcc, exec, s[8:9]
	v_mov_b32_e32 v139, 1.0
	s_cbranch_vccnz .LBB0_460
	v_mov_b32_e32 v139, v81
	v_lshl_add_u64 v[140:141], v[138:139], 2, s[14:15]
	global_load_dword v240, v[140:141], off
	global_load_dword v241, v[140:141], off offset:64
	global_load_dword v242, v[140:141], off offset:128
	global_load_dword v243, v[140:141], off offset:192
	global_load_dword v244, v[140:141], off offset:512
	global_load_dword v245, v[140:141], off offset:576
	global_load_dword v246, v[140:141], off offset:640
	global_load_dword v247, v[140:141], off offset:704
	s_waitcnt vmcnt(0)
	v_mov_b32_e32 v80, v240
	v_fmamk_f32 v80, v80, 0x3a800000, v147
	v_rsq_f32_e32 v139, v80
.LBB0_460:
	s_nop 0
	v_mul_f32_e32 v140, v126, v139
	v_mul_f32_e32 v140, 0xbfb8aa3b, v140
	v_exp_f32_e32 v140, v140
	v_mul_lo_u32 v80, v138, 24
	v_lshl_add_u32 v80, v157, 3, v80
	s_and_b64 vcc, exec, s[6:7]
	v_add_f32_e32 v140, 1.0, v140
	v_rcp_f32_e32 v158, v140
	v_mul_f32_e32 v140, v127, v139
	v_mul_f32_e32 v140, 0xbfb8aa3b, v140
	v_exp_f32_e32 v140, v140
	s_nop 0
	v_add_f32_e32 v140, 1.0, v140
	v_rcp_f32_e32 v159, v140
	v_mul_f32_e32 v140, v128, v139
	v_mul_f32_e32 v140, 0xbfb8aa3b, v140
	v_exp_f32_e32 v140, v140
	s_nop 0
	v_add_f32_e32 v140, 1.0, v140
	v_rcp_f32_e32 v160, v140
	v_mul_f32_e32 v140, v129, v139
	v_mul_f32_e32 v140, 0xbfb8aa3b, v140
	v_exp_f32_e32 v140, v140
	s_nop 0
	v_add_f32_e32 v140, 1.0, v140
	v_rcp_f32_e32 v161, v140
	v_lshl_add_u64 v[140:141], v[80:81], 2, s[20:21]
	global_store_dwordx4 v[140:141], v[158:161], off
	v_mul_f32_e32 v140, v122, v139
	v_mul_f32_e32 v140, 0xbfb8aa3b, v140
	v_exp_f32_e32 v140, v140
	v_mov_b32_e32 v141, v81
	v_add_f32_e32 v140, 1.0, v140
	v_rcp_f32_e32 v158, v140
	v_mul_f32_e32 v140, v123, v139
	v_mul_f32_e32 v140, 0xbfb8aa3b, v140
	v_exp_f32_e32 v140, v140
	s_nop 0
	v_add_f32_e32 v140, 1.0, v140
	v_rcp_f32_e32 v159, v140
	v_mul_f32_e32 v140, v124, v139
	v_mul_f32_e32 v139, v125, v139
	v_mul_f32_e32 v140, 0xbfb8aa3b, v140
	v_mul_f32_e32 v139, 0xbfb8aa3b, v139
	v_exp_f32_e32 v140, v140
	v_exp_f32_e32 v139, v139
	v_add_f32_e32 v140, 1.0, v140
	v_add_f32_e32 v139, 1.0, v139
	v_rcp_f32_e32 v160, v140
	v_rcp_f32_e32 v161, v139
	v_or_b32_e32 v140, 4, v80
	v_lshl_add_u64 v[140:141], v[140:141], 2, s[20:21]
	global_store_dwordx4 v[140:141], v[158:161], off
	s_cbranch_vccnz .LBB0_462
	v_add_u32_e32 v140, 16, v138
	v_mov_b32_e32 v141, v81
	v_lshl_add_u64 v[140:141], v[140:141], 2, s[14:15]
	v_mov_b32_e32 v139, v241
	v_fmamk_f32 v139, v139, 0x3a800000, v147
	v_rsq_f32_e32 v143, v139
.LBB0_462:
	s_nop 0
	v_mul_f32_e32 v139, v110, v143
	v_mul_f32_e32 v139, 0xbfb8aa3b, v139
	v_exp_f32_e32 v141, v139
	v_add_u32_e32 v140, 0x180, v80
	v_add_u32_e32 v80, 0x184, v80
	v_mov_b32_e32 v139, 1.0
	v_add_f32_e32 v141, 1.0, v141
	v_rcp_f32_e32 v158, v141
	v_mul_f32_e32 v141, v111, v143
	v_mul_f32_e32 v141, 0xbfb8aa3b, v141
	v_exp_f32_e32 v141, v141
	s_and_b64 vcc, exec, s[6:7]
	v_add_f32_e32 v141, 1.0, v141
	v_rcp_f32_e32 v159, v141
	v_mul_f32_e32 v141, v112, v143
	v_mul_f32_e32 v141, 0xbfb8aa3b, v141
	v_exp_f32_e32 v141, v141
	s_nop 0
	v_add_f32_e32 v141, 1.0, v141
	v_rcp_f32_e32 v160, v141
	v_mul_f32_e32 v141, v113, v143
	v_mul_f32_e32 v141, 0xbfb8aa3b, v141
	v_exp_f32_e32 v141, v141
	s_nop 0
	v_add_f32_e32 v141, 1.0, v141
	v_rcp_f32_e32 v161, v141
	v_mov_b32_e32 v141, v81
	v_lshl_add_u64 v[144:145], v[140:141], 2, s[20:21]
	v_mul_f32_e32 v141, v106, v143
	v_mul_f32_e32 v141, 0xbfb8aa3b, v141
	v_exp_f32_e32 v141, v141
	global_store_dwordx4 v[144:145], v[158:161], off
	v_lshl_add_u64 v[144:145], v[80:81], 2, s[20:21]
	v_add_f32_e32 v141, 1.0, v141
	v_rcp_f32_e32 v158, v141
	v_mul_f32_e32 v141, v107, v143
	v_mul_f32_e32 v141, 0xbfb8aa3b, v141
	v_exp_f32_e32 v141, v141
	s_nop 0
	v_add_f32_e32 v141, 1.0, v141
	v_rcp_f32_e32 v159, v141
	v_mul_f32_e32 v141, v108, v143
	v_mul_f32_e32 v141, 0xbfb8aa3b, v141
	v_exp_f32_e32 v141, v141
	s_nop 0
	v_add_f32_e32 v141, 1.0, v141
	v_rcp_f32_e32 v160, v141
	v_mul_f32_e32 v141, v109, v143
	v_mul_f32_e32 v141, 0xbfb8aa3b, v141
	v_exp_f32_e32 v141, v141
	s_nop 0
	v_add_f32_e32 v141, 1.0, v141
	v_rcp_f32_e32 v161, v141
	v_mov_b32_e32 v141, 1.0
	global_store_dwordx4 v[144:145], v[158:161], off
	s_cbranch_vccnz .LBB0_464
	v_add_u32_e32 v80, 32, v138
	v_lshl_add_u64 v[144:145], v[80:81], 2, s[14:15]
	v_mov_b32_e32 v80, v242
	v_fmamk_f32 v80, v80, 0x3a800000, v147
	v_rsq_f32_e32 v141, v80
; __device__ __forceinline__ float sigmoidf_(float x) { return __builtin_amdgcn_rcpf(1.0f + __expf(-x)); }
;     __device__ __forceinline__ void operator()(const f32x4 (&acc)[2][2][4][2], const pg8::Unit& u, int wr, int wc, int fr_, int fq_) const {
;     ...
;                     for (int m = 0; m < 4; ++m) { const unsigned row = (unsigned)(u.pm * 256 + 128 * ai + 64 * wr + 16 * m + fr);
;                         const float rin = rsq ? __builtin_amdgcn_rsqf(rsq[row] * (1.0f / DM) + 1e-6f) : 1.0f;
; #pragma unroll
;                         for (int n = 0; n < 2; ++n) { f32x4 y;
; #pragma unroll
;                             for (int e = 0; e < 4; ++e) y[e] = sigmoidf_(acc[ai][0][m][n][e] * rin);
;                             *(f32x4*)(nsg + (row * 24u + (unsigned)(8 * fq + 4 * n))) = y; } }
.LBB0_464:
	s_nop 0
	v_mul_f32_e32 v143, v94, v141
	v_mul_f32_e32 v143, 0xbfb8aa3b, v143
	v_exp_f32_e32 v143, v143
	v_add_u32_e32 v80, 0x180, v140
	v_lshl_add_u64 v[144:145], v[80:81], 2, s[20:21]
	v_add_u32_e32 v140, 0x184, v140
	v_add_f32_e32 v143, 1.0, v143
	v_rcp_f32_e32 v158, v143
	v_mul_f32_e32 v143, v95, v141
	v_mul_f32_e32 v143, 0xbfb8aa3b, v143
	v_exp_f32_e32 v143, v143
	s_and_b64 vcc, exec, s[6:7]
	v_add_f32_e32 v143, 1.0, v143
	v_rcp_f32_e32 v159, v143
	v_mul_f32_e32 v143, v96, v141
	v_mul_f32_e32 v143, 0xbfb8aa3b, v143
	v_exp_f32_e32 v143, v143
	s_nop 0
	v_add_f32_e32 v143, 1.0, v143
	v_rcp_f32_e32 v160, v143
	v_mul_f32_e32 v143, v97, v141
	v_mul_f32_e32 v143, 0xbfb8aa3b, v143
	v_exp_f32_e32 v143, v143
	s_nop 0
	v_add_f32_e32 v143, 1.0, v143
	v_rcp_f32_e32 v161, v143
	v_mul_f32_e32 v143, v90, v141
	v_mul_f32_e32 v143, 0xbfb8aa3b, v143
	v_exp_f32_e32 v143, v143
	global_store_dwordx4 v[144:145], v[158:161], off
	v_add_f32_e32 v143, 1.0, v143
	s_nop 0
	v_rcp_f32_e32 v158, v143
	v_mul_f32_e32 v143, v91, v141
	v_mul_f32_e32 v143, 0xbfb8aa3b, v143
	v_exp_f32_e32 v143, v143
	s_nop 0
	v_add_f32_e32 v143, 1.0, v143
	v_rcp_f32_e32 v159, v143
	v_mul_f32_e32 v143, v92, v141
	v_mul_f32_e32 v141, v93, v141
	v_mul_f32_e32 v143, 0xbfb8aa3b, v143
	v_mul_f32_e32 v141, 0xbfb8aa3b, v141
	v_exp_f32_e32 v143, v143
	v_exp_f32_e32 v141, v141
	v_add_f32_e32 v143, 1.0, v143
	v_add_f32_e32 v141, 1.0, v141
	v_rcp_f32_e32 v160, v143
	v_rcp_f32_e32 v161, v141
	v_mov_b32_e32 v141, v81
	v_lshl_add_u64 v[140:141], v[140:141], 2, s[20:21]
	global_store_dwordx4 v[140:141], v[158:161], off
	s_cbranch_vccnz .LBB0_466
	v_add_u32_e32 v140, 48, v138
	v_mov_b32_e32 v141, v81
	v_lshl_add_u64 v[140:141], v[140:141], 2, s[14:15]
	v_mov_b32_e32 v139, v243
	v_fmamk_f32 v139, v139, 0x3a800000, v147
	v_rsq_f32_e32 v139, v139
.LBB0_466:
	s_nop 0
	v_mul_f32_e32 v141, v76, v139
	v_mul_f32_e32 v141, 0xbfb8aa3b, v141
	v_exp_f32_e32 v141, v141
	v_add_u32_e32 v140, 0x180, v80
	v_add_u32_e32 v80, 0x184, v80
	v_mov_b32_e32 v143, 1.0
	v_add_f32_e32 v141, 1.0, v141
	v_rcp_f32_e32 v158, v141
	v_mul_f32_e32 v141, v77, v139
	v_mul_f32_e32 v141, 0xbfb8aa3b, v141
	v_exp_f32_e32 v141, v141
	s_and_b64 vcc, exec, s[6:7]
	v_add_f32_e32 v141, 1.0, v141
	v_rcp_f32_e32 v159, v141
	v_mul_f32_e32 v141, v78, v139
	v_mul_f32_e32 v141, 0xbfb8aa3b, v141
	v_exp_f32_e32 v141, v141
	s_nop 0
	v_add_f32_e32 v141, 1.0, v141
	v_rcp_f32_e32 v160, v141
	v_mul_f32_e32 v141, v79, v139
	v_mul_f32_e32 v141, 0xbfb8aa3b, v141
	v_exp_f32_e32 v141, v141
	s_nop 0
	v_add_f32_e32 v141, 1.0, v141
	v_rcp_f32_e32 v161, v141
	v_mov_b32_e32 v141, v81
	v_lshl_add_u64 v[144:145], v[140:141], 2, s[20:21]
	v_mul_f32_e32 v141, v72, v139
	v_mul_f32_e32 v141, 0xbfb8aa3b, v141
	v_exp_f32_e32 v141, v141
	global_store_dwordx4 v[144:145], v[158:161], off
	v_lshl_add_u64 v[144:145], v[80:81], 2, s[20:21]
	v_add_f32_e32 v141, 1.0, v141
	v_rcp_f32_e32 v158, v141
	v_mul_f32_e32 v141, v73, v139
	v_mul_f32_e32 v141, 0xbfb8aa3b, v141
	v_exp_f32_e32 v141, v141
	s_nop 0
	v_add_f32_e32 v141, 1.0, v141
	v_rcp_f32_e32 v159, v141
	v_mul_f32_e32 v141, v74, v139
	v_mul_f32_e32 v139, v75, v139
	v_mul_f32_e32 v141, 0xbfb8aa3b, v141
	v_mul_f32_e32 v139, 0xbfb8aa3b, v139
	v_exp_f32_e32 v141, v141
	v_exp_f32_e32 v139, v139
	v_add_f32_e32 v141, 1.0, v141
	v_add_f32_e32 v139, 1.0, v139
	v_rcp_f32_e32 v160, v141
	v_rcp_f32_e32 v161, v139
	v_mov_b32_e32 v139, 1.0
	global_store_dwordx4 v[144:145], v[158:161], off
	s_cbranch_vccnz .LBB0_468
	v_add_u32_e32 v80, 0x80, v138
	v_lshl_add_u64 v[144:145], v[80:81], 2, s[14:15]
	v_mov_b32_e32 v80, v244
	v_fmamk_f32 v80, v80, 0x3a800000, v147
	v_rsq_f32_e32 v139, v80
.LBB0_468:
	s_nop 0
	v_mul_f32_e32 v141, v60, v139
	v_mul_f32_e32 v141, 0xbfb8aa3b, v141
	v_exp_f32_e32 v141, v141
	v_add_u32_e32 v80, 0x780, v140
	v_lshl_add_u64 v[144:145], v[80:81], 2, s[20:21]
	v_add_u32_e32 v140, 0x784, v140
	v_add_f32_e32 v141, 1.0, v141
	v_rcp_f32_e32 v158, v141
	v_mul_f32_e32 v141, v61, v139
	v_mul_f32_e32 v141, 0xbfb8aa3b, v141
	v_exp_f32_e32 v141, v141
	s_and_b64 vcc, exec, s[6:7]
	v_add_f32_e32 v141, 1.0, v141
	v_rcp_f32_e32 v159, v141
	v_mul_f32_e32 v141, v62, v139
	v_mul_f32_e32 v141, 0xbfb8aa3b, v141
	v_exp_f32_e32 v141, v141
	s_nop 0
	v_add_f32_e32 v141, 1.0, v141
	v_rcp_f32_e32 v160, v141
	v_mul_f32_e32 v141, v63, v139
	v_mul_f32_e32 v141, 0xbfb8aa3b, v141
	v_exp_f32_e32 v141, v141
	s_nop 0
	v_add_f32_e32 v141, 1.0, v141
	v_rcp_f32_e32 v161, v141
	v_mul_f32_e32 v141, v56, v139
	v_mul_f32_e32 v141, 0xbfb8aa3b, v141
	v_exp_f32_e32 v141, v141
	global_store_dwordx4 v[144:145], v[158:161], off
	v_add_f32_e32 v141, 1.0, v141
	s_nop 0
	v_rcp_f32_e32 v158, v141
	v_mul_f32_e32 v141, v57, v139
	v_mul_f32_e32 v141, 0xbfb8aa3b, v141
	v_exp_f32_e32 v141, v141
	s_nop 0
	v_add_f32_e32 v141, 1.0, v141
	v_rcp_f32_e32 v159, v141
	v_mul_f32_e32 v141, v58, v139
	v_mul_f32_e32 v139, v59, v139
	v_mul_f32_e32 v141, 0xbfb8aa3b, v141
	v_mul_f32_e32 v139, 0xbfb8aa3b, v139
	v_exp_f32_e32 v141, v141
	v_exp_f32_e32 v139, v139
	v_add_f32_e32 v141, 1.0, v141
	v_add_f32_e32 v139, 1.0, v139
	v_rcp_f32_e32 v160, v141
	v_rcp_f32_e32 v161, v139
	v_mov_b32_e32 v141, v81
	v_lshl_add_u64 v[140:141], v[140:141], 2, s[20:21]
	global_store_dwordx4 v[140:141], v[158:161], off
	s_cbranch_vccnz .LBB0_470
	v_add_u32_e32 v140, 0x90, v138
	v_mov_b32_e32 v141, v81
	v_lshl_add_u64 v[140:141], v[140:141], 2, s[14:15]
	v_mov_b32_e32 v139, v245
	v_fmamk_f32 v139, v139, 0x3a800000, v147
	v_rsq_f32_e32 v143, v139
; __device__ __forceinline__ float sigmoidf_(float x) { return __builtin_amdgcn_rcpf(1.0f + __expf(-x)); }
;     __device__ __forceinline__ void operator()(const f32x4 (&acc)[2][2][4][2], const pg8::Unit& u, int wr, int wc, int fr_, int fq_) const {
;     ...
;                     for (int m = 0; m < 4; ++m) { const unsigned row = (unsigned)(u.pm * 256 + 128 * ai + 64 * wr + 16 * m + fr);
;                         const float rin = rsq ? __builtin_amdgcn_rsqf(rsq[row] * (1.0f / DM) + 1e-6f) : 1.0f;
; #pragma unroll
;                         for (int n = 0; n < 2; ++n) { f32x4 y;
; #pragma unroll
;                             for (int e = 0; e < 4; ++e) y[e] = sigmoidf_(acc[ai][0][m][n][e] * rin);
;                             *(f32x4*)(nsg + (row * 24u + (unsigned)(8 * fq + 4 * n))) = y; } }
.LBB0_470:
	s_nop 0
	v_mul_f32_e32 v139, v44, v143
	v_mul_f32_e32 v139, 0xbfb8aa3b, v139
	v_exp_f32_e32 v141, v139
	v_add_u32_e32 v140, 0x180, v80
	v_add_u32_e32 v80, 0x184, v80
	v_mov_b32_e32 v139, 1.0
	v_add_f32_e32 v141, 1.0, v141
	v_rcp_f32_e32 v158, v141
	v_mul_f32_e32 v141, v45, v143
	v_mul_f32_e32 v141, 0xbfb8aa3b, v141
	v_exp_f32_e32 v141, v141
	s_and_b64 vcc, exec, s[6:7]
	v_add_f32_e32 v141, 1.0, v141
	v_rcp_f32_e32 v159, v141
	v_mul_f32_e32 v141, v46, v143
	v_mul_f32_e32 v141, 0xbfb8aa3b, v141
	v_exp_f32_e32 v141, v141
	s_nop 0
	v_add_f32_e32 v141, 1.0, v141
	v_rcp_f32_e32 v160, v141
	v_mul_f32_e32 v141, v47, v143
	v_mul_f32_e32 v141, 0xbfb8aa3b, v141
	v_exp_f32_e32 v141, v141
	s_nop 0
	v_add_f32_e32 v141, 1.0, v141
	v_rcp_f32_e32 v161, v141
	v_mov_b32_e32 v141, v81
	v_lshl_add_u64 v[144:145], v[140:141], 2, s[20:21]
	v_mul_f32_e32 v141, v40, v143
	v_mul_f32_e32 v141, 0xbfb8aa3b, v141
	v_exp_f32_e32 v141, v141
	global_store_dwordx4 v[144:145], v[158:161], off
	v_lshl_add_u64 v[144:145], v[80:81], 2, s[20:21]
	v_add_f32_e32 v141, 1.0, v141
	v_rcp_f32_e32 v158, v141
	v_mul_f32_e32 v141, v41, v143
	v_mul_f32_e32 v141, 0xbfb8aa3b, v141
	v_exp_f32_e32 v141, v141
	s_nop 0
	v_add_f32_e32 v141, 1.0, v141
	v_rcp_f32_e32 v159, v141
	v_mul_f32_e32 v141, v42, v143
	v_mul_f32_e32 v141, 0xbfb8aa3b, v141
	v_exp_f32_e32 v141, v141
	s_nop 0
	v_add_f32_e32 v141, 1.0, v141
	v_rcp_f32_e32 v160, v141
	v_mul_f32_e32 v141, v43, v143
	v_mul_f32_e32 v141, 0xbfb8aa3b, v141
	v_exp_f32_e32 v141, v141
	s_nop 0
	v_add_f32_e32 v141, 1.0, v141
	v_rcp_f32_e32 v161, v141
	v_mov_b32_e32 v141, 1.0
	global_store_dwordx4 v[144:145], v[158:161], off
	s_cbranch_vccnz .LBB0_472
	v_add_u32_e32 v80, 0xa0, v138
	v_lshl_add_u64 v[144:145], v[80:81], 2, s[14:15]
	v_mov_b32_e32 v80, v246
	v_fmamk_f32 v80, v80, 0x3a800000, v147
	v_rsq_f32_e32 v141, v80
.LBB0_472:
	s_nop 0
	v_mul_f32_e32 v143, v28, v141
	v_mul_f32_e32 v143, 0xbfb8aa3b, v143
	v_exp_f32_e32 v143, v143
	v_add_u32_e32 v80, 0x180, v140
	v_lshl_add_u64 v[144:145], v[80:81], 2, s[20:21]
	v_add_u32_e32 v140, 0x184, v140
	v_add_f32_e32 v143, 1.0, v143
	v_rcp_f32_e32 v158, v143
	v_mul_f32_e32 v143, v29, v141
	v_mul_f32_e32 v143, 0xbfb8aa3b, v143
	v_exp_f32_e32 v143, v143
	s_and_b64 vcc, exec, s[6:7]
	v_add_f32_e32 v143, 1.0, v143
	v_rcp_f32_e32 v159, v143
	v_mul_f32_e32 v143, v30, v141
	v_mul_f32_e32 v143, 0xbfb8aa3b, v143
	v_exp_f32_e32 v143, v143
	s_nop 0
	v_add_f32_e32 v143, 1.0, v143
	v_rcp_f32_e32 v160, v143
	v_mul_f32_e32 v143, v31, v141
	v_mul_f32_e32 v143, 0xbfb8aa3b, v143
	v_exp_f32_e32 v143, v143
	s_nop 0
	v_add_f32_e32 v143, 1.0, v143
	v_rcp_f32_e32 v161, v143
	v_mul_f32_e32 v143, v24, v141
	v_mul_f32_e32 v143, 0xbfb8aa3b, v143
	v_exp_f32_e32 v143, v143
	global_store_dwordx4 v[144:145], v[158:161], off
	v_add_f32_e32 v143, 1.0, v143
	s_nop 0
	v_rcp_f32_e32 v158, v143
	v_mul_f32_e32 v143, v25, v141
	v_mul_f32_e32 v143, 0xbfb8aa3b, v143
	v_exp_f32_e32 v143, v143
	s_nop 0
	v_add_f32_e32 v143, 1.0, v143
	v_rcp_f32_e32 v159, v143
	v_mul_f32_e32 v143, v26, v141
	v_mul_f32_e32 v141, v27, v141
	v_mul_f32_e32 v143, 0xbfb8aa3b, v143
	v_mul_f32_e32 v141, 0xbfb8aa3b, v141
	v_exp_f32_e32 v143, v143
	v_exp_f32_e32 v141, v141
	v_add_f32_e32 v143, 1.0, v143
	v_add_f32_e32 v141, 1.0, v141
	v_rcp_f32_e32 v160, v143
	v_rcp_f32_e32 v161, v141
	v_mov_b32_e32 v141, v81
	v_lshl_add_u64 v[140:141], v[140:141], 2, s[20:21]
	global_store_dwordx4 v[140:141], v[158:161], off
	s_cbranch_vccnz .LBB0_474
	v_add_u32_e32 v138, 0xb0, v138
	v_mov_b32_e32 v139, v81
	v_lshl_add_u64 v[138:139], v[138:139], 2, s[14:15]
	v_mov_b32_e32 v138, v247
	v_fmamk_f32 v138, v138, 0x3a800000, v147
	v_rsq_f32_e32 v139, v138

; __device__ __forceinline__ float bf2f(unsigned v16) { return __uint_as_float(v16 << 16); }
; __global__ void __launch_bounds__(512, 2) hybrid_fwd(Params P) {
;     ...
;             if (bx < 128) { const int kv = bx >> 6, ks = (bx >> 4) & 3;
;                 pg8::Gemm g{(const bf16_t*)(ws + WS_B + (kv ? HB_VCR : HB_KCR) * MiB) + ks * 512, (const bf16_t*)(ws + WS_WC1) + (size_t)kv * 256 * 2048 + ks * 512, 4096, 256, 512, 1024, 2048};
;                 pg8::StaticOrder S; S.init(4096, 256, G, bx & 15);
;                 EpiStoreF32 E{(float*)(ws + WS_H) + (size_t)(kv * 4 + ks) * 4096 * 256};
;     ...
;                 pg8::gemm_phase<EpiStoreF32, pg8::StaticOrder, true, true>(lds, g, S, E, tid);
;     ...
;             } else {
;                 const bf16_t* mbk = (const bf16_t*)(ws + WS_B + HB_MBK * MiB); float* KMEAN = (float*)(ws + WS_SMALL + 4096);
;                 for (int item = (bx - 128) * 8 + wave; item < 512; item += (G - 128) * 8) { const int bh = item >> 5, n = item & 31;
;                     const bf16_t* kp = mbk + ((size_t)bh * SEQ + 256 * n) * 64 + lane; float a = 0.f;
; #pragma unroll 8
;                     for (int j = 0; j < 256; ++j) a += bf2f(kp[(size_t)j * 64]);
;                     KMEAN[(size_t)item * 64 + lane] = a * (1.0f / 256.0f); }
.LBB0_740:
	s_nop 0
	s_nop 0
	s_nop 0
	s_nop 0
	s_or_b64 exec, exec, s[4:5]
	v_readlane_b32 s4, v255, 17
	s_barrier
	s_mov_b64 s[6:7], s[58:59]
	s_mov_b32 s28, s69
	s_mov_b32 s10, s2
	v_mov_b32_e32 v8, v146
	s_cmpk_gt_i32 s10, 0x7f
	v_readfirstlane_b32 s8, v8
	s_mov_b64 s[4:5], -1
	s_cbranch_scc0 .LBB0_747
	s_ashr_i32 s4, s8, 6
	s_lshl_b32 s5, s10, 3
	s_add_i32 s4, s5, s4
	s_addk_i32 s4, 0xfc00
	s_cmpk_gt_i32 s4, 0x1ff
	s_cbranch_scc1 .LBB0_746
	v_and_b32_e32 v2, 63, v8
	v_lshlrev_b32_e32 v80, 2, v2
	v_lshl_add_u64 v[0:1], s[6:7], 0, v[80:81]
	s_mov_b64 s[8:9], 0x2401000
	v_lshlrev_b32_e32 v80, 1, v2
	v_lshl_add_u64 v[0:1], v[0:1], 0, s[8:9]
	s_lshl_b32 s11, s28, 3
	v_lshl_add_u64 v[2:3], s[6:7], 0, v[80:81]
	s_mov_b64 s[8:9], 0x17100200
	s_lshl_b32 s13, s28, 17
	s_addk_i32 s11, 0xfc00
	v_lshl_add_u64 v[2:3], v[2:3], 0, s[8:9]
	s_lshl_b32 s12, s4, 14
	s_add_i32 s13, s13, 0xff000000
